# prompt attention item: the 8 Q-fragment global loads issued before the K/V LDS staging (above the barrier) instead of after it
# baseline (speedup 1.0000x reference)
.LBB0_553:
	s_or_b64 exec, exec, s[22:23]
	s_ashr_i32 s98, s25, 7
	s_lshl_b32 s99, s27, 2
	s_add_i32 s98, s98, s99
	s_lshl_b32 s98, s98, 6
	s_ashr_i32 s99, s98, 31
	s_lshl_b64 s[98:99], s[98:99], 1
	s_add_u32 s100, s10, s98
	s_addc_u32 s101, s11, s99
	s_and_b32 s32, s25, 64
	v_and_b32_e32 v216, 15, v32
	v_bfe_u32 v217, v32, 4, 2
	v_or_b32_e32 v218, s24, v62
	v_or_b32_e32 v219, s32, v216
	v_lshlrev_b32_e32 v220, 4, v217
	v_mov_b32_e32 v221, 0
	v_lshl_add_u64 v[220:221], s[100:101], 0, v[220:221]
	v_or_b32_e32 v219, v219, v218
	v_mul_lo_u32 v222, v63, s18
	v_mad_u64_u32 v[224:225], s[98:99], v219, s18, v[220:221]
	v_add_u32_e32 v225, v222, v225
	global_load_dwordx4 v[184:187], v[224:225], off
	global_load_dwordx4 v[188:191], v[224:225], off offset:64
	v_or_b32_e32 v223, 16, v219
	v_mad_u64_u32 v[224:225], s[98:99], v223, s18, v[220:221]
	v_add_u32_e32 v225, v222, v225
	global_load_dwordx4 v[192:195], v[224:225], off
	global_load_dwordx4 v[196:199], v[224:225], off offset:64
	v_or_b32_e32 v223, 32, v219
	v_mad_u64_u32 v[224:225], s[98:99], v223, s18, v[220:221]
	v_add_u32_e32 v225, v222, v225
	global_load_dwordx4 v[200:203], v[224:225], off
	global_load_dwordx4 v[204:207], v[224:225], off offset:64
	v_or_b32_e32 v223, 48, v219
	v_mad_u64_u32 v[224:225], s[98:99], v223, s18, v[220:221]
	v_add_u32_e32 v225, v222, v225
	global_load_dwordx4 v[208:211], v[224:225], off
	global_load_dwordx4 v[212:215], v[224:225], off offset:64
	s_lshl_b32 s16, s27, 2
	s_cmp_eq_u32 s26, 0
	v_mul_lo_u32 v36, v33, s97
	s_cselect_b64 s[62:63], -1, 0
	s_cmp_lg_u32 s26, 0
	v_add_u32_e32 v36, 0, v36
	s_cselect_b64 s[54:55], -1, 0
	v_lshl_add_u32 v34, v34, 6, v36
	s_movk_i32 s4, 0xff72
	s_ashr_i32 s17, s25, 7
	s_waitcnt vmcnt(15)
	ds_write_b128 v34, v[0:3]
	s_waitcnt vmcnt(14)
	ds_write_b128 v34, v[20:23] offset:16
	s_waitcnt vmcnt(13)
	ds_write_b128 v34, v[24:27] offset:32
	s_waitcnt vmcnt(12)
	ds_write_b128 v34, v[28:31] offset:48
	v_mul_lo_u32 v0, v33, s4
	v_mul_i32_i24_e32 v1, 0x210, v35
	s_add_i32 s20, s17, s16
	v_add3_u32 v0, v36, v0, v1
	s_add_i32 s16, s20, 1
	s_waitcnt vmcnt(11)
	ds_write_b16 v0, v12 offset:36864
	ds_write_b16_d16_hi v0, v12 offset:37392
	ds_write_b16 v0, v13 offset:37920
	ds_write_b16_d16_hi v0, v13 offset:38448
	ds_write_b16 v0, v14 offset:38976
	ds_write_b16_d16_hi v0, v14 offset:39504
	ds_write_b16 v0, v15 offset:40032
	ds_write_b16_d16_hi v0, v15 offset:40560
	s_waitcnt vmcnt(10)
	ds_write_b16 v0, v16 offset:41088
	ds_write_b16_d16_hi v0, v16 offset:41616
	ds_write_b16 v0, v17 offset:42144
	ds_write_b16_d16_hi v0, v17 offset:42672
	ds_write_b16 v0, v18 offset:43200
	ds_write_b16_d16_hi v0, v18 offset:43728
	ds_write_b16 v0, v19 offset:44256
	ds_write_b16_d16_hi v0, v19 offset:44784
	s_waitcnt vmcnt(9)
	ds_write_b16 v0, v8 offset:45312
	ds_write_b16_d16_hi v0, v8 offset:45840
	ds_write_b16 v0, v9 offset:46368
	ds_write_b16_d16_hi v0, v9 offset:46896
	ds_write_b16 v0, v10 offset:47424
	ds_write_b16_d16_hi v0, v10 offset:47952
	ds_write_b16 v0, v11 offset:48480
	ds_write_b16_d16_hi v0, v11 offset:49008
	s_waitcnt vmcnt(8)
	ds_write_b16 v0, v4 offset:49536
	ds_write_b16_d16_hi v0, v4 offset:50064
	ds_write_b16 v0, v5 offset:50592
	ds_write_b16_d16_hi v0, v5 offset:51120
	ds_write_b16 v0, v6 offset:51648
	ds_write_b16_d16_hi v0, v6 offset:52176
	ds_write_b16 v0, v7 offset:52704
	ds_write_b16_d16_hi v0, v7 offset:53232
	v_cvt_f32_i32_e32 v0, s16
	s_mov_b32 s16, 0x42fc0000
	s_and_b32 s4, s25, 64
	s_waitcnt lgkmcnt(0)
	v_cmp_lt_f32_e32 vcc, s16, v0
	s_and_b64 s[16:17], vcc, exec
	s_cselect_b32 s16, 0xffffffc0, 0
	v_cndmask_b32_e32 v1, 0, v242, vcc
	v_sub_f32_e32 v0, v1, v0
	v_exp_f32_e32 v0, v0
	s_barrier
	v_and_b32_e32 v61, 15, v32
	v_ldexp_f32 v24, v0, s16
	s_add_i32 s16, s20, s58
	s_ashr_i32 s17, s16, 31
	s_lshl_b64 s[16:17], s[16:17], 2
	s_add_u32 s12, s12, s16
	s_addc_u32 s13, s13, s17
	global_load_dword v25, v175, s[12:13]
	s_lshl_b32 s12, s20, 6
	s_ashr_i32 s13, s12, 31
	s_lshl_b64 s[76:77], s[12:13], 1
	v_bfe_u32 v100, v32, 4, 2
	s_add_u32 s10, s10, s76
	v_or_b32_e32 v4, s24, v62
	v_or_b32_e32 v90, s4, v61
	s_addc_u32 s11, s11, s77
	v_lshlrev_b32_e32 v174, 4, v100
	v_lshl_add_u64 v[0:1], s[10:11], 0, v[174:175]
	v_or_b32_e32 v62, v90, v4
	v_mad_u64_u32 v[2:3], s[10:11], v62, s18, v[0:1]
	v_mul_lo_u32 v6, v63, s18
	v_or_b32_e32 v99, 16, v90
	v_add_u32_e32 v3, v6, v3
	v_or_b32_e32 v86, v4, v99
	s_waitcnt vmcnt(1)
	v_mov_b32_e32 v44, v184
	v_mov_b32_e32 v45, v185
	v_mov_b32_e32 v46, v186
	v_mov_b32_e32 v47, v187
	v_mov_b32_e32 v48, v188
	v_mov_b32_e32 v49, v189
	v_mov_b32_e32 v50, v190
	v_mov_b32_e32 v51, v191
	v_mad_u64_u32 v[2:3], s[10:11], v86, s18, v[0:1]
	v_add_u32_e32 v3, v6, v3
	v_or_b32_e32 v82, 32, v62
	v_or_b32_e32 v60, 48, v62
	v_mov_b32_e32 v16, v192
	v_mov_b32_e32 v17, v193
	v_mov_b32_e32 v18, v194
	v_mov_b32_e32 v19, v195
	v_mov_b32_e32 v20, v196
	v_mov_b32_e32 v21, v197
	v_mov_b32_e32 v22, v198
	v_mov_b32_e32 v23, v199
	v_mad_u64_u32 v[2:3], s[10:11], v82, s18, v[0:1]
	v_mad_u64_u32 v[4:5], s[10:11], v60, s18, v[0:1]
	v_add_u32_e32 v3, v6, v3
	v_add_u32_e32 v5, v6, v5
	v_mov_b32_e32 v8, v200
	v_mov_b32_e32 v9, v201
	v_mov_b32_e32 v10, v202
	v_mov_b32_e32 v11, v203
	v_mov_b32_e32 v12, v204
	v_mov_b32_e32 v13, v205
	v_mov_b32_e32 v14, v206
	v_mov_b32_e32 v15, v207
	s_nop 0
	v_mov_b32_e32 v0, v208
	v_mov_b32_e32 v1, v209
	v_mov_b32_e32 v2, v210
	v_mov_b32_e32 v3, v211
	s_nop 0
	v_mov_b32_e32 v4, v212
	v_mov_b32_e32 v5, v213
	v_mov_b32_e32 v6, v214
	v_mov_b32_e32 v7, v215
	v_lshlrev_b32_e32 v73, 2, v100
	s_mov_b32 s10, 2.0
	v_mul_f32_e32 v64, 0x3fb8aa3b, v24
	s_mov_b32 s11, 0x40400000
	v_add_u32_e32 v83, 0, v174
	v_or_b32_e32 v69, 0x80, v90
	v_or_b32_e32 v87, s4, v73
	v_or_b32_e32 v85, 1, v73
	v_or_b32_e32 v77, 2, v73
	v_or_b32_e32 v75, 3, v73
	v_pk_mul_f32 v[78:79], v[64:65], s[10:11] op_sel_hi:[0,1]
	s_mov_b64 s[10:11], -1
	s_and_b64 vcc, exec, s[54:55]
	v_mad_u32_u24 v98, v90, s97, v83
	v_cmp_lt_u32_e64 s[22:23], v73, v61
	v_xor_b32_e32 v176, 0x80000000, v64
	v_cmp_le_u32_e64 s[24:25], v73, v61
	v_sub_u32_e32 v71, v69, v87
	v_mul_f32_e32 v84, 0, v64
	v_mul_f32_e32 v80, 0x41800000, v64
	v_mul_f32_e32 v76, 0x42000000, v64
	v_mul_f32_e32 v74, 0x42400000, v64
	v_mul_f32_e32 v72, 0x42800000, v64
	v_mul_f32_e32 v70, 0x42a00000, v64
	v_mul_f32_e32 v68, 0x42c00000, v64
	v_mul_f32_e32 v66, 0x42e00000, v64
	v_cmp_ge_u32_e64 s[36:37], v85, v61
	v_cmp_ge_u32_e64 s[30:31], v77, v61
	v_cmp_ge_u32_e64 s[34:35], v75, v61
	v_cmp_le_u32_e64 s[26:27], v77, v61
	v_cmp_le_u32_e64 s[28:29], v75, v61
	s_waitcnt vmcnt(0)
	v_mul_f32_e32 v67, 0x3fb8aa3b, v25
	s_cbranch_vccz .LBB0_555
	v_cvt_f32_ubyte0_e32 v88, v71
	ds_read_b128 v[24:27], v98
	ds_read_b128 v[28:31], v98 offset:64
	v_mov_b32_e32 v89, v64
	v_pk_mul_f32 v[96:97], v[88:89], v[176:177]
	s_mov_b64 s[10:11], 0
	v_add_f32_e32 v111, v64, v96
	v_mov_b32_e32 v110, v96
	v_pk_add_f32 v[142:143], v[78:79], v[96:97] op_sel_hi:[1,0]
	v_pk_add_f32 v[32:33], v[110:111], v[84:85] op_sel_hi:[1,0]
	v_pk_add_f32 v[34:35], v[84:85], v[142:143] op_sel_hi:[0,1]
	v_pk_add_f32 v[132:133], v[110:111], v[72:73] op_sel_hi:[1,0]
	v_pk_add_f32 v[134:135], v[72:73], v[142:143] op_sel_hi:[0,1]
	s_waitcnt vmcnt(7) lgkmcnt(1)
	v_mfma_f32_16x16x32_bf16 v[24:27], v[24:27], v[44:47], v[32:35]
	v_add_f32_e64 v136, v110, v68
	v_add_f32_e64 v137, v111, v68
	v_pk_add_f32 v[138:139], v[68:69], v[142:143] op_sel_hi:[0,1]
	ds_read_b128 v[32:35], v98 offset:2304
	s_waitcnt vmcnt(6) lgkmcnt(1)
	v_mfma_f32_16x16x32_bf16 v[36:39], v[28:31], v[48:51], v[24:27]
	v_add_f32_e64 v28, v110, v80
	v_add_f32_e64 v29, v111, v80
	v_pk_add_f32 v[30:31], v[80:81], v[142:143] op_sel_hi:[0,1]
	ds_read_b128 v[24:27], v98 offset:2368
	s_waitcnt lgkmcnt(1)
	v_mfma_f32_16x16x32_bf16 v[28:31], v[32:35], v[44:47], v[28:31]
	ds_read_b128 v[32:35], v98 offset:4608
	ds_read_b128 v[40:43], v98 offset:4672
	ds_read_b128 v[92:95], v98 offset:6912
	ds_read_b128 v[102:105], v98 offset:6976
	s_waitcnt lgkmcnt(4)
	v_mfma_f32_16x16x32_bf16 v[52:55], v[24:27], v[48:51], v[28:31]
	v_add_f32_e64 v24, v110, v76
	v_add_f32_e64 v25, v111, v76
	v_pk_add_f32 v[26:27], v[76:77], v[142:143] op_sel_hi:[0,1]
	ds_read_b128 v[28:31], v98 offset:9216
	ds_read_b128 v[106:109], v98 offset:9280
	s_waitcnt lgkmcnt(5)
	v_mfma_f32_16x16x32_bf16 v[24:27], v[32:35], v[44:47], v[24:27]
	ds_read_b128 v[32:35], v98 offset:11520
	ds_read_b128 v[112:115], v98 offset:11584
	ds_read_b128 v[116:119], v98 offset:13824
	ds_read_b128 v[120:123], v98 offset:13888
	s_waitcnt lgkmcnt(8)
	v_mfma_f32_16x16x32_bf16 v[56:59], v[40:43], v[48:51], v[24:27]
	ds_read_b128 v[40:43], v98 offset:16128
	ds_read_b128 v[124:127], v98 offset:16192
	s_nop 0
	v_pk_add_f32 v[24:25], v[110:111], v[74:75] op_sel_hi:[1,0]
	v_pk_add_f32 v[26:27], v[74:75], v[142:143] op_sel_hi:[0,1]
	s_waitcnt lgkmcnt(7)
	v_mfma_f32_16x16x32_bf16 v[28:31], v[28:31], v[44:47], v[132:135]
	v_mfma_f32_16x16x32_bf16 v[24:27], v[92:95], v[44:47], v[24:27]
	s_nop 1
	v_add_f32_e64 v132, v110, v66
	v_add_f32_e64 v133, v111, v66
	ds_read_b128 v[92:95], v98 offset:18432
	ds_read_b128 v[128:131], v98 offset:18496
	v_pk_add_f32 v[134:135], v[66:67], v[142:143] op_sel_hi:[0,1]
	v_mfma_f32_16x16x32_bf16 v[24:27], v[102:105], v[48:51], v[24:27]
	v_add_f32_e64 v102, v110, v70
	v_add_f32_e64 v103, v111, v70
	v_mov_b32_e32 v110, v97
	v_pk_fma_f32 v[140:141], v[88:89], v[176:177], v[110:111]
	s_waitcnt lgkmcnt(8)
	v_mfma_f32_16x16x32_bf16 v[28:31], v[106:109], v[48:51], v[28:31]
	v_cndmask_b32_e64 v110, v36, v243, s[22:23]
	v_cndmask_b32_e64 v109, v243, v37, s[36:37]
	v_max3_f32 v36, v67, v110, v109
	v_cndmask_b32_e64 v111, v243, v38, s[30:31]
	v_cndmask_b32_e64 v108, v243, v39, s[34:35]
	v_pk_add_f32 v[104:105], v[70:71], v[142:143] op_sel_hi:[0,1]
	v_max3_f32 v36, v36, v111, v108
	v_max3_f32 v65, v36, v52, v53
	s_waitcnt lgkmcnt(7)
	v_mfma_f32_16x16x32_bf16 v[32:35], v[32:35], v[44:47], v[102:105]
	v_max3_f32 v65, v65, v54, v55
	v_max3_f32 v65, v65, v56, v57
	v_max3_f32 v65, v65, v58, v59
	s_waitcnt lgkmcnt(5)
	v_mfma_f32_16x16x32_bf16 v[36:39], v[116:119], v[44:47], v[136:139]
	v_max3_f32 v65, v65, v24, v25
	v_pk_add_f32 v[142:143], v[96:97], v[142:143] op_sel:[1,0]
	v_max3_f32 v65, v65, v26, v27
	v_mfma_f32_16x16x32_bf16 v[32:35], v[112:115], v[48:51], v[32:35]
	v_max3_f32 v65, v65, v28, v29
	v_max3_f32 v65, v65, v30, v31
	s_waitcnt lgkmcnt(3)
	v_mfma_f32_16x16x32_bf16 v[40:43], v[40:43], v[44:47], v[132:135]
	s_waitcnt lgkmcnt(1)
	v_mfma_f32_16x16x32_bf16 v[92:95], v[92:95], v[44:47], v[140:143]
	s_nop 1
	v_max3_f32 v65, v65, v32, v33
	v_max3_f32 v65, v65, v34, v35
	v_mfma_f32_16x16x32_bf16 v[36:39], v[120:123], v[48:51], v[36:39]
	v_mfma_f32_16x16x32_bf16 v[40:43], v[124:127], v[48:51], v[40:43]
	s_waitcnt lgkmcnt(0)
	v_mfma_f32_16x16x32_bf16 v[92:95], v[128:131], v[48:51], v[92:95]
	s_nop 4
	v_max3_f32 v65, v65, v36, v37
	v_max3_f32 v65, v65, v38, v39
	v_max3_f32 v65, v65, v40, v41
	v_max3_f32 v65, v65, v42, v43
	v_cndmask_b32_e64 v101, v243, v92, s[24:25]
	v_cndmask_b32_e64 v89, v243, v93, s[22:23]
	v_max3_f32 v65, v65, v101, v89
	v_cndmask_b32_e64 v104, v243, v94, s[26:27]
	v_cndmask_b32_e64 v103, v243, v95, s[28:29]
	v_max3_f32 v112, v65, v104, v103
